# grid barrier: non-leader workgroups poll the top-level generation word directly (one fewer hop); leader no longer bumps the per-XCD generation word
# speedup vs baseline: 1.0018x; 1.0010x over previous
.LBB0_160:
	s_or_b64 exec, exec, s[8:9]
	v_cvt_f32_u32_e32 v5, v3
	s_waitcnt vmcnt(0)
	v_readfirstlane_b32 s6, v4
	v_sub_u32_e32 v4, 0, v3
	v_rcp_iflag_f32_e32 v5, v5
	v_add_u32_e32 v6, s6, v2
	v_mul_f32_e32 v5, 0x4f7ffffe, v5
	v_cvt_u32_f32_e32 v5, v5
	v_mul_lo_u32 v2, v4, v5
	v_mul_hi_u32 v2, v5, v2
	v_add_u32_e32 v2, v5, v2
	v_mul_hi_u32 v2, v6, v2
	v_mul_lo_u32 v4, v2, v3
	v_sub_u32_e32 v4, v6, v4
	v_add_u32_e32 v5, 1, v2
	v_cmp_ge_u32_e32 vcc, v4, v3
	s_nop 1
	v_cndmask_b32_e32 v2, v2, v5, vcc
	v_sub_u32_e32 v5, v4, v3
	v_cndmask_b32_e32 v4, v4, v5, vcc
	v_add_u32_e32 v5, 1, v2
	v_cmp_ge_u32_e32 vcc, v4, v3
	v_add_u32_e32 v4, 1, v6
	s_nop 0
	v_cndmask_b32_e32 v2, v2, v5, vcc
	v_mul_lo_u32 v5, v3, v2
	v_add_u32_e32 v3, v5, v3
	v_cmp_ne_u32_e32 vcc, v4, v3
	s_and_saveexec_b64 s[6:7], vcc
	s_xor_b64 s[6:7], exec, s[6:7]
	s_cbranch_execz .LBB0_174
	s_waitcnt lgkmcnt(0)
	s_add_u32 s12, s94, 0xb3d5900
	s_addc_u32 s13, s95, 0
	v_mov_b32_e32 v1, 0
	global_load_dword v1, v1, s[12:13] sc1
	s_waitcnt vmcnt(0)
	v_cmp_eq_u32_e32 vcc, v1, v2
	s_and_saveexec_b64 s[8:9], vcc
	s_cbranch_execz .LBB0_173
	s_add_u32 s10, s94, 0xb3d2600
	s_addc_u32 s11, s95, 0
	s_mov_b32 s24, 1
	s_mov_b64 s[14:15], 0
	v_mov_b32_e32 v1, 0
	s_branch .LBB0_164

.LBB0_191:
	s_or_b64 exec, exec, s[6:7]
	s_mov_b64 s[6:7], exec
	v_mbcnt_lo_u32_b32 v1, s6, 0
	v_mbcnt_hi_u32_b32 v1, s7, v1
	v_cmp_eq_u32_e32 vcc, 0, v1
	s_waitcnt vmcnt(0)
	buffer_inv sc1
	s_and_saveexec_b64 s[8:9], vcc
	s_cbranch_execz .LBB0_193
	s_bcnt1_i32_b64 s6, s[6:7]
	v_mov_b32_e32 v1, 0x2000
	v_mov_b32_e32 v2, s6
.LBB0_193:
	s_or_b64 exec, exec, s[8:9]
	s_waitcnt vmcnt(0)

.LBB0_544:
	s_or_b64 exec, exec, s[8:9]
	v_cvt_f32_u32_e32 v6, v4
	s_waitcnt vmcnt(0)
	v_readfirstlane_b32 s6, v5
	v_sub_u32_e32 v5, 0, v4
	v_rcp_iflag_f32_e32 v6, v6
	v_add_u32_e32 v7, s6, v3
	v_mul_f32_e32 v6, 0x4f7ffffe, v6
	v_cvt_u32_f32_e32 v6, v6
	v_mul_lo_u32 v3, v5, v6
	v_mul_hi_u32 v3, v6, v3
	v_add_u32_e32 v3, v6, v3
	v_mul_hi_u32 v3, v7, v3
	v_mul_lo_u32 v5, v3, v4
	v_sub_u32_e32 v5, v7, v5
	v_add_u32_e32 v6, 1, v3
	v_cmp_ge_u32_e32 vcc, v5, v4
	s_nop 1
	v_cndmask_b32_e32 v3, v3, v6, vcc
	v_sub_u32_e32 v6, v5, v4
	v_cndmask_b32_e32 v5, v5, v6, vcc
	v_add_u32_e32 v6, 1, v3
	v_cmp_ge_u32_e32 vcc, v5, v4
	v_add_u32_e32 v5, 1, v7
	s_nop 0
	v_cndmask_b32_e32 v3, v3, v6, vcc
	v_mul_lo_u32 v6, v4, v3
	v_add_u32_e32 v4, v6, v4
	v_cmp_ne_u32_e32 vcc, v5, v4
	s_and_saveexec_b64 s[6:7], vcc
	s_xor_b64 s[6:7], exec, s[6:7]
	s_cbranch_execz .LBB0_558
	s_waitcnt lgkmcnt(0)
	s_add_u32 s12, s94, 0xb3d5900
	s_addc_u32 s13, s95, 0
	v_mov_b32_e32 v2, 0
	global_load_dword v2, v2, s[12:13] sc1
	s_waitcnt vmcnt(0)
	v_cmp_eq_u32_e32 vcc, v2, v3
	s_and_saveexec_b64 s[8:9], vcc
	s_cbranch_execz .LBB0_557
	s_add_u32 s10, s94, 0xb3d2600
	s_addc_u32 s11, s95, 0
	s_mov_b32 s24, 1
	s_mov_b64 s[14:15], 0
	v_mov_b32_e32 v2, 0
	s_branch .LBB0_548

.LBB0_575:
	s_or_b64 exec, exec, s[6:7]
	s_mov_b64 s[6:7], exec
	v_mbcnt_lo_u32_b32 v2, s6, 0
	v_mbcnt_hi_u32_b32 v2, s7, v2
	v_cmp_eq_u32_e32 vcc, 0, v2
	s_waitcnt vmcnt(0)
	buffer_inv sc1
	s_and_saveexec_b64 s[8:9], vcc
	s_cbranch_execz .LBB0_577
	s_bcnt1_i32_b64 s6, s[6:7]
	v_mov_b32_e32 v2, 0x2000
	v_mov_b32_e32 v3, s6
.LBB0_577:
	s_or_b64 exec, exec, s[8:9]
	s_waitcnt vmcnt(0)

.LBB0_687:
	s_or_b64 exec, exec, s[6:7]
	s_mov_b64 s[6:7], exec
	v_mbcnt_lo_u32_b32 v2, s6, 0
	v_mbcnt_hi_u32_b32 v2, s7, v2
	v_cmp_eq_u32_e32 vcc, 0, v2
	s_waitcnt vmcnt(0)
	buffer_inv sc1
	s_and_saveexec_b64 s[8:9], vcc
	s_cbranch_execz .LBB0_689
	s_bcnt1_i32_b64 s6, s[6:7]
	v_mov_b32_e32 v2, 0x2000
	v_mov_b32_e32 v3, s6
.LBB0_689:
	s_or_b64 exec, exec, s[8:9]
	s_waitcnt vmcnt(0)

.LBB0_746:
	s_or_b64 exec, exec, s[6:7]
	s_mov_b64 s[6:7], exec
	v_mbcnt_lo_u32_b32 v2, s6, 0
	v_mbcnt_hi_u32_b32 v2, s7, v2
	v_cmp_eq_u32_e32 vcc, 0, v2
	s_waitcnt vmcnt(0)
	buffer_inv sc1
	s_and_saveexec_b64 s[8:9], vcc
	s_cbranch_execz .LBB0_748
	s_bcnt1_i32_b64 s6, s[6:7]
	v_mov_b32_e32 v2, 0x2000
	v_mov_b32_e32 v3, s6
.LBB0_748:
	s_or_b64 exec, exec, s[8:9]
	s_waitcnt vmcnt(0)

.LBB0_805:
	s_or_b64 exec, exec, s[6:7]
	s_mov_b64 s[6:7], exec
	v_mbcnt_lo_u32_b32 v2, s6, 0
	v_mbcnt_hi_u32_b32 v2, s7, v2
	v_cmp_eq_u32_e32 vcc, 0, v2
	s_waitcnt vmcnt(0)
	buffer_inv sc1
	s_and_saveexec_b64 s[8:9], vcc
	s_cbranch_execz .LBB0_807
	s_bcnt1_i32_b64 s6, s[6:7]
	v_mov_b32_e32 v2, 0x2000
	v_mov_b32_e32 v3, s6
.LBB0_807:
	s_or_b64 exec, exec, s[8:9]
	s_waitcnt vmcnt(0)

.LBB0_893:
	s_or_b64 exec, exec, s[6:7]
	s_mov_b64 s[6:7], exec
	v_mbcnt_lo_u32_b32 v1, s6, 0
	v_mbcnt_hi_u32_b32 v1, s7, v1
	v_cmp_eq_u32_e32 vcc, 0, v1
	s_waitcnt vmcnt(0)
	buffer_inv sc1
	s_and_saveexec_b64 s[8:9], vcc
	s_cbranch_execz .LBB0_895
	s_bcnt1_i32_b64 s6, s[6:7]
	v_mov_b32_e32 v1, 0x2000
	v_mov_b32_e32 v2, s6
.LBB0_895:
	s_or_b64 exec, exec, s[8:9]
	s_waitcnt vmcnt(0)

.LBB0_1001:
	s_or_b64 exec, exec, s[6:7]
	s_mov_b64 s[6:7], exec
	v_mbcnt_lo_u32_b32 v1, s6, 0
	v_mbcnt_hi_u32_b32 v1, s7, v1
	v_cmp_eq_u32_e32 vcc, 0, v1
	s_waitcnt vmcnt(0)
	buffer_inv sc1
	s_and_saveexec_b64 s[8:9], vcc
	s_cbranch_execz .LBB0_1003
	s_bcnt1_i32_b64 s6, s[6:7]
	v_mov_b32_e32 v1, 0x2000
	v_mov_b32_e32 v2, s6
.LBB0_1003:
	s_or_b64 exec, exec, s[8:9]
	s_waitcnt vmcnt(0)

.LBB0_1069:
	s_or_b64 exec, exec, s[6:7]
	s_mov_b64 s[6:7], exec
	v_mbcnt_lo_u32_b32 v1, s6, 0
	v_mbcnt_hi_u32_b32 v1, s7, v1
	v_cmp_eq_u32_e32 vcc, 0, v1
	s_waitcnt vmcnt(0)
	buffer_inv sc1
	s_and_saveexec_b64 s[8:9], vcc
	s_cbranch_execz .LBB0_1071
	s_bcnt1_i32_b64 s6, s[6:7]
	v_mov_b32_e32 v1, 0x2000
	v_mov_b32_e32 v2, s6
.LBB0_1071:
	s_or_b64 exec, exec, s[8:9]
	s_waitcnt vmcnt(0)

.LBB0_1128:
	s_or_b64 exec, exec, s[6:7]
	v_cvt_f32_u32_e32 v5, v3
	s_waitcnt vmcnt(0)
	v_readfirstlane_b32 s4, v4
	v_sub_u32_e32 v4, 0, v3
	v_rcp_iflag_f32_e32 v5, v5
	v_add_u32_e32 v6, s4, v2
	v_mul_f32_e32 v5, 0x4f7ffffe, v5
	v_cvt_u32_f32_e32 v5, v5
	v_mul_lo_u32 v2, v4, v5
	v_mul_hi_u32 v2, v5, v2
	v_add_u32_e32 v2, v5, v2
	v_mul_hi_u32 v2, v6, v2
	v_mul_lo_u32 v4, v2, v3
	v_sub_u32_e32 v4, v6, v4
	v_add_u32_e32 v5, 1, v2
	v_cmp_ge_u32_e32 vcc, v4, v3
	s_nop 1
	v_cndmask_b32_e32 v2, v2, v5, vcc
	v_sub_u32_e32 v5, v4, v3
	v_cndmask_b32_e32 v4, v4, v5, vcc
	v_add_u32_e32 v5, 1, v2
	v_cmp_ge_u32_e32 vcc, v4, v3
	v_add_u32_e32 v4, 1, v6
	s_nop 0
	v_cndmask_b32_e32 v2, v2, v5, vcc
	v_mul_lo_u32 v5, v3, v2
	v_add_u32_e32 v3, v5, v3
	v_cmp_ne_u32_e32 vcc, v4, v3
	s_and_saveexec_b64 s[4:5], vcc
	s_xor_b64 s[4:5], exec, s[4:5]
	s_cbranch_execz .LBB0_1142
	s_waitcnt lgkmcnt(0)
	s_add_u32 s10, s94, 0xb3d5900
	s_addc_u32 s11, s95, 0
	v_mov_b32_e32 v1, 0
	global_load_dword v1, v1, s[10:11] sc1
	s_waitcnt vmcnt(0)
	v_cmp_eq_u32_e32 vcc, v1, v2
	s_and_saveexec_b64 s[6:7], vcc
	s_cbranch_execz .LBB0_1141
	s_add_u32 s8, s94, 0xb3d2600
	s_addc_u32 s9, s95, 0
	s_mov_b32 s22, 1
	s_mov_b64 s[12:13], 0
	v_mov_b32_e32 v1, 0
	s_branch .LBB0_1132

.LBB0_1159:
	s_or_b64 exec, exec, s[4:5]
	s_mov_b64 s[4:5], exec
	v_mbcnt_lo_u32_b32 v1, s4, 0
	v_mbcnt_hi_u32_b32 v1, s5, v1
	v_cmp_eq_u32_e32 vcc, 0, v1
	s_waitcnt vmcnt(0)
	buffer_inv sc1
	s_and_saveexec_b64 s[6:7], vcc
	s_cbranch_execz .LBB0_1161
	s_bcnt1_i32_b64 s4, s[4:5]
	v_mov_b32_e32 v1, 0x2000
	v_mov_b32_e32 v2, s4
.LBB0_1161:
	s_or_b64 exec, exec, s[6:7]
	s_waitcnt vmcnt(0)

.LBB0_1258:
	s_or_b64 exec, exec, s[6:7]
	s_mov_b64 s[6:7], exec
	v_mbcnt_lo_u32_b32 v1, s6, 0
	v_mbcnt_hi_u32_b32 v1, s7, v1
	v_cmp_eq_u32_e32 vcc, 0, v1
	s_waitcnt vmcnt(0)
	buffer_inv sc1
	s_and_saveexec_b64 s[8:9], vcc
	s_cbranch_execz .LBB0_1260
	s_bcnt1_i32_b64 s6, s[6:7]
	v_mov_b32_e32 v1, 0x2000
	v_mov_b32_e32 v2, s6
.LBB0_1260:
	s_or_b64 exec, exec, s[8:9]
	s_waitcnt vmcnt(0)
